# all queries (NSA and SWA): RoPE applied in registers at the attention unit's Q load; rope phase rotates only the 5 key heads
# speedup vs baseline: 1.0106x; 1.0082x over previous
.LBB0_333:
	v_lshrrev_b32_e32 v58, 7, v26
	v_lshlrev_b32_e32 v58, 12, v58
	v_and_b32_e32 v59, 2, v26
	v_lshlrev_b32_e32 v59, 9, v59
	v_or_b32_e32 v58, v58, v59
	v_and_b32_e32 v59, 1, v26
	v_lshlrev_b32_e32 v59, 4, v59
	v_or_b32_e32 v58, v58, v59
	v_bfe_u32 v59, v26, 2, 5
	v_lshlrev_b32_e32 v59, 5, v59
	v_or_b32_e32 v58, v58, v59
	v_add_co_u32_e32 v60, vcc, v56, v58
	s_nop 1
	v_addc_co_u32_e32 v61, vcc, 0, v57, vcc
	v_ashrrev_i32_e32 v22, 2, v26
	v_ashrrev_i32_e32 v23, 31, v22
	v_lshlrev_b32_e32 v0, 3, v26
	v_and_b32_e32 v24, 24, v0
	v_lshlrev_b64 v[2:3], 8, v[22:23]
	v_lshl_add_u64 v[2:3], v[20:21], 0, v[2:3]
	v_lshlrev_b32_e32 v0, 3, v24
	v_lshl_add_u64 v[14:15], v[2:3], 0, v[0:1]
	global_load_dwordx4 v[2:5], v[14:15], off
	global_load_dwordx4 v[6:9], v[14:15], off offset:16
	global_load_dwordx4 v[10:13], v[14:15], off offset:32
	s_nop 0
	global_load_dwordx4 v[14:17], v[14:15], off offset:48
	v_mad_i64_i32 v[22:23], s[8:9], v22, s61, v[18:19]
	v_lshlrev_b32_e32 v0, 1, v24
	v_lshl_add_u64 v[22:23], v[22:23], 0, v[0:1]
	s_mov_b32 s10, 0
	s_movk_i32 s11, 0x200
	s_movk_i32 s12, 0x100
	s_waitcnt vmcnt(0) lgkmcnt(0)
	v_mov_b32_e32 v24, v15
	v_mov_b32_e32 v25, v17
	v_mov_b32_e32 v15, v16
	v_mov_b32_e32 v16, v11
	v_mov_b32_e32 v17, v13
	v_mov_b32_e32 v11, v12
	v_mov_b32_e32 v12, v7
	v_mov_b32_e32 v13, v9
	v_mov_b32_e32 v7, v8
	v_mov_b32_e32 v8, v3
	v_mov_b32_e32 v9, v5
	v_mov_b32_e32 v3, v4
	s_movk_i32 s74, 0x300
	v_lshl_add_u64 v[4:5], s[74:75], 1, v[22:23]
	s_and_b32 s98, s74, 64
	s_lshl_b32 s98, s98, 16
	v_lshl_add_u64 v[62:63], v[60:61], 0, s[98:99]
	global_load_dwordx4 v[28:31], v[4:5], off
	global_load_dwordx4 v[32:35], v[4:5], off offset:64
	s_waitcnt vmcnt(0) lgkmcnt(0)
	v_lshlrev_b32_e32 v36, 16, v28
	v_lshlrev_b32_e32 v38, 16, v32
	v_and_b32_e32 v39, 0xffff0000, v32
	v_and_b32_e32 v37, 0xffff0000, v28
	v_pk_mul_f32 v[40:41], v[2:3], v[38:39]
	v_pk_mul_f32 v[38:39], v[8:9], v[38:39]
	v_lshlrev_b32_e32 v32, 16, v33
	v_and_b32_e32 v33, 0xffff0000, v33
	v_pk_fma_f32 v[40:41], v[8:9], v[36:37], v[40:41]
	v_pk_fma_f32 v[36:37], v[2:3], v[36:37], v[38:39] neg_lo:[0,0,1] neg_hi:[0,0,1]
	v_lshlrev_b32_e32 v28, 16, v29
	v_and_b32_e32 v29, 0xffff0000, v29
	v_pk_mul_f32 v[38:39], v[6:7], v[32:33]
	v_pk_mul_f32 v[32:33], v[12:13], v[32:33]
	v_lshlrev_b32_e32 v42, 16, v34
	v_and_b32_e32 v43, 0xffff0000, v34
	v_pk_fma_f32 v[38:39], v[12:13], v[28:29], v[38:39]
	v_pk_fma_f32 v[32:33], v[6:7], v[28:29], v[32:33] neg_lo:[0,0,1] neg_hi:[0,0,1]
	v_lshlrev_b32_e32 v28, 16, v30
	v_and_b32_e32 v29, 0xffff0000, v30
	v_pk_mul_f32 v[44:45], v[10:11], v[42:43]
	v_pk_mul_f32 v[42:43], v[16:17], v[42:43]
	v_pk_fma_f32 v[44:45], v[16:17], v[28:29], v[44:45]
	v_pk_fma_f32 v[42:43], v[10:11], v[28:29], v[42:43] neg_lo:[0,0,1] neg_hi:[0,0,1]
	v_lshlrev_b32_e32 v28, 16, v31
	v_and_b32_e32 v29, 0xffff0000, v31
	v_lshlrev_b32_e32 v30, 16, v35
	v_and_b32_e32 v31, 0xffff0000, v35
	v_pk_mul_f32 v[34:35], v[14:15], v[30:31]
	v_pk_mul_f32 v[30:31], v[24:25], v[30:31]
	v_pk_fma_f32 v[34:35], v[24:25], v[28:29], v[34:35]
	v_pk_fma_f32 v[46:47], v[14:15], v[28:29], v[30:31] neg_lo:[0,0,1] neg_hi:[0,0,1]
	v_cvt_pk_bf16_f32 v28, v36, v37
	v_cvt_pk_bf16_f32 v29, v32, v33
	v_cvt_pk_bf16_f32 v30, v42, v43
	v_cvt_pk_bf16_f32 v31, v46, v47
	global_store_dwordx4 v[4:5], v[28:31], off
	global_store_dwordx4 v[62:63], v[28:31], off
	s_nop 1
	v_cvt_pk_bf16_f32 v28, v40, v41
	v_cvt_pk_bf16_f32 v29, v38, v39
	v_cvt_pk_bf16_f32 v30, v44, v45
	v_cvt_pk_bf16_f32 v31, v34, v35
	global_store_dwordx4 v[4:5], v[28:31], off offset:64
	global_store_dwordx4 v[62:63], v[28:31], off offset:2048
	s_movk_i32 s74, 0x340
	v_lshl_add_u64 v[4:5], s[74:75], 1, v[22:23]
	s_and_b32 s98, s74, 64
	s_lshl_b32 s98, s98, 16
	v_lshl_add_u64 v[62:63], v[60:61], 0, s[98:99]
	global_load_dwordx4 v[28:31], v[4:5], off
	global_load_dwordx4 v[32:35], v[4:5], off offset:64
	s_waitcnt vmcnt(0) lgkmcnt(0)
	v_lshlrev_b32_e32 v36, 16, v28
	v_lshlrev_b32_e32 v38, 16, v32
	v_and_b32_e32 v39, 0xffff0000, v32
	v_and_b32_e32 v37, 0xffff0000, v28
	v_pk_mul_f32 v[40:41], v[2:3], v[38:39]
	v_pk_mul_f32 v[38:39], v[8:9], v[38:39]
	v_lshlrev_b32_e32 v32, 16, v33
	v_and_b32_e32 v33, 0xffff0000, v33
	v_pk_fma_f32 v[40:41], v[8:9], v[36:37], v[40:41]
	v_pk_fma_f32 v[36:37], v[2:3], v[36:37], v[38:39] neg_lo:[0,0,1] neg_hi:[0,0,1]
	v_lshlrev_b32_e32 v28, 16, v29
	v_and_b32_e32 v29, 0xffff0000, v29
	v_pk_mul_f32 v[38:39], v[6:7], v[32:33]
	v_pk_mul_f32 v[32:33], v[12:13], v[32:33]
	v_lshlrev_b32_e32 v42, 16, v34
	v_and_b32_e32 v43, 0xffff0000, v34
	v_pk_fma_f32 v[38:39], v[12:13], v[28:29], v[38:39]
	v_pk_fma_f32 v[32:33], v[6:7], v[28:29], v[32:33] neg_lo:[0,0,1] neg_hi:[0,0,1]
	v_lshlrev_b32_e32 v28, 16, v30
	v_and_b32_e32 v29, 0xffff0000, v30
	v_pk_mul_f32 v[44:45], v[10:11], v[42:43]
	v_pk_mul_f32 v[42:43], v[16:17], v[42:43]
	v_pk_fma_f32 v[44:45], v[16:17], v[28:29], v[44:45]
	v_pk_fma_f32 v[42:43], v[10:11], v[28:29], v[42:43] neg_lo:[0,0,1] neg_hi:[0,0,1]
	v_lshlrev_b32_e32 v28, 16, v31
	v_and_b32_e32 v29, 0xffff0000, v31
	v_lshlrev_b32_e32 v30, 16, v35
	v_and_b32_e32 v31, 0xffff0000, v35
	v_pk_mul_f32 v[34:35], v[14:15], v[30:31]
	v_pk_mul_f32 v[30:31], v[24:25], v[30:31]
	v_pk_fma_f32 v[34:35], v[24:25], v[28:29], v[34:35]
	v_pk_fma_f32 v[46:47], v[14:15], v[28:29], v[30:31] neg_lo:[0,0,1] neg_hi:[0,0,1]
	v_cvt_pk_bf16_f32 v28, v36, v37
	v_cvt_pk_bf16_f32 v29, v32, v33
	v_cvt_pk_bf16_f32 v30, v42, v43
	v_cvt_pk_bf16_f32 v31, v46, v47
	global_store_dwordx4 v[4:5], v[28:31], off
	global_store_dwordx4 v[62:63], v[28:31], off
	s_nop 1
	v_cvt_pk_bf16_f32 v28, v40, v41
	v_cvt_pk_bf16_f32 v29, v38, v39
	v_cvt_pk_bf16_f32 v30, v44, v45
	v_cvt_pk_bf16_f32 v31, v34, v35
	global_store_dwordx4 v[4:5], v[28:31], off offset:64
	global_store_dwordx4 v[62:63], v[28:31], off offset:2048
	s_movk_i32 s74, 0x400
	v_lshl_add_u64 v[4:5], s[74:75], 1, v[22:23]
	global_load_dwordx4 v[28:31], v[4:5], off
	global_load_dwordx4 v[32:35], v[4:5], off offset:64
	s_waitcnt vmcnt(0) lgkmcnt(0)
	v_lshlrev_b32_e32 v36, 16, v28
	v_lshlrev_b32_e32 v38, 16, v32
	v_and_b32_e32 v39, 0xffff0000, v32
	v_and_b32_e32 v37, 0xffff0000, v28
	v_pk_mul_f32 v[40:41], v[2:3], v[38:39]
	v_pk_mul_f32 v[38:39], v[8:9], v[38:39]
	v_lshlrev_b32_e32 v32, 16, v33
	v_and_b32_e32 v33, 0xffff0000, v33
	v_pk_fma_f32 v[40:41], v[8:9], v[36:37], v[40:41]
	v_pk_fma_f32 v[36:37], v[2:3], v[36:37], v[38:39] neg_lo:[0,0,1] neg_hi:[0,0,1]
	v_lshlrev_b32_e32 v28, 16, v29
	v_and_b32_e32 v29, 0xffff0000, v29
	v_pk_mul_f32 v[38:39], v[6:7], v[32:33]
	v_pk_mul_f32 v[32:33], v[12:13], v[32:33]
	v_lshlrev_b32_e32 v42, 16, v34
	v_and_b32_e32 v43, 0xffff0000, v34
	v_pk_fma_f32 v[38:39], v[12:13], v[28:29], v[38:39]
	v_pk_fma_f32 v[32:33], v[6:7], v[28:29], v[32:33] neg_lo:[0,0,1] neg_hi:[0,0,1]
	v_lshlrev_b32_e32 v28, 16, v30
	v_and_b32_e32 v29, 0xffff0000, v30
	v_pk_mul_f32 v[44:45], v[10:11], v[42:43]
	v_pk_mul_f32 v[42:43], v[16:17], v[42:43]
	v_pk_fma_f32 v[44:45], v[16:17], v[28:29], v[44:45]
	v_pk_fma_f32 v[42:43], v[10:11], v[28:29], v[42:43] neg_lo:[0,0,1] neg_hi:[0,0,1]
	v_lshlrev_b32_e32 v28, 16, v31
	v_and_b32_e32 v29, 0xffff0000, v31
	v_lshlrev_b32_e32 v30, 16, v35
	v_and_b32_e32 v31, 0xffff0000, v35
	v_pk_mul_f32 v[34:35], v[14:15], v[30:31]
	v_pk_mul_f32 v[30:31], v[24:25], v[30:31]
	v_pk_fma_f32 v[34:35], v[24:25], v[28:29], v[34:35]
	v_pk_fma_f32 v[46:47], v[14:15], v[28:29], v[30:31] neg_lo:[0,0,1] neg_hi:[0,0,1]
	v_cvt_pk_bf16_f32 v28, v36, v37
	v_cvt_pk_bf16_f32 v29, v32, v33
	v_cvt_pk_bf16_f32 v30, v42, v43
	v_cvt_pk_bf16_f32 v31, v46, v47
	global_store_dwordx4 v[4:5], v[28:31], off
	s_nop 1
	v_cvt_pk_bf16_f32 v28, v40, v41
	v_cvt_pk_bf16_f32 v29, v38, v39
	v_cvt_pk_bf16_f32 v30, v44, v45
	v_cvt_pk_bf16_f32 v31, v34, v35
	global_store_dwordx4 v[4:5], v[28:31], off offset:64
	s_movk_i32 s74, 0x440
	v_lshl_add_u64 v[4:5], s[74:75], 1, v[22:23]
	global_load_dwordx4 v[28:31], v[4:5], off
	global_load_dwordx4 v[32:35], v[4:5], off offset:64
	s_waitcnt vmcnt(0) lgkmcnt(0)
	v_lshlrev_b32_e32 v36, 16, v28
	v_lshlrev_b32_e32 v38, 16, v32
	v_and_b32_e32 v39, 0xffff0000, v32
	v_and_b32_e32 v37, 0xffff0000, v28
	v_pk_mul_f32 v[40:41], v[2:3], v[38:39]
	v_pk_mul_f32 v[38:39], v[8:9], v[38:39]
	v_lshlrev_b32_e32 v32, 16, v33
	v_and_b32_e32 v33, 0xffff0000, v33
	v_pk_fma_f32 v[40:41], v[8:9], v[36:37], v[40:41]
	v_pk_fma_f32 v[36:37], v[2:3], v[36:37], v[38:39] neg_lo:[0,0,1] neg_hi:[0,0,1]
	v_lshlrev_b32_e32 v28, 16, v29
	v_and_b32_e32 v29, 0xffff0000, v29
	v_pk_mul_f32 v[38:39], v[6:7], v[32:33]
	v_pk_mul_f32 v[32:33], v[12:13], v[32:33]
	v_lshlrev_b32_e32 v42, 16, v34
	v_and_b32_e32 v43, 0xffff0000, v34
	v_pk_fma_f32 v[38:39], v[12:13], v[28:29], v[38:39]
	v_pk_fma_f32 v[32:33], v[6:7], v[28:29], v[32:33] neg_lo:[0,0,1] neg_hi:[0,0,1]
	v_lshlrev_b32_e32 v28, 16, v30
	v_and_b32_e32 v29, 0xffff0000, v30
	v_pk_mul_f32 v[44:45], v[10:11], v[42:43]
	v_pk_mul_f32 v[42:43], v[16:17], v[42:43]
	v_pk_fma_f32 v[44:45], v[16:17], v[28:29], v[44:45]
	v_pk_fma_f32 v[42:43], v[10:11], v[28:29], v[42:43] neg_lo:[0,0,1] neg_hi:[0,0,1]
	v_lshlrev_b32_e32 v28, 16, v31
	v_and_b32_e32 v29, 0xffff0000, v31
	v_lshlrev_b32_e32 v30, 16, v35
	v_and_b32_e32 v31, 0xffff0000, v35
	v_pk_mul_f32 v[34:35], v[14:15], v[30:31]
	v_pk_mul_f32 v[30:31], v[24:25], v[30:31]
	v_pk_fma_f32 v[34:35], v[24:25], v[28:29], v[34:35]
	v_pk_fma_f32 v[46:47], v[14:15], v[28:29], v[30:31] neg_lo:[0,0,1] neg_hi:[0,0,1]
	v_cvt_pk_bf16_f32 v28, v36, v37
	v_cvt_pk_bf16_f32 v29, v32, v33
	v_cvt_pk_bf16_f32 v30, v42, v43
	v_cvt_pk_bf16_f32 v31, v46, v47
	global_store_dwordx4 v[4:5], v[28:31], off
	s_nop 1
	v_cvt_pk_bf16_f32 v28, v40, v41
	v_cvt_pk_bf16_f32 v29, v38, v39
	v_cvt_pk_bf16_f32 v30, v44, v45
	v_cvt_pk_bf16_f32 v31, v34, v35
	global_store_dwordx4 v[4:5], v[28:31], off offset:64
	s_movk_i32 s74, 0x700
	v_lshl_add_u64 v[4:5], s[74:75], 1, v[22:23]
	global_load_dwordx4 v[28:31], v[4:5], off
	global_load_dwordx4 v[32:35], v[4:5], off offset:64
	s_waitcnt vmcnt(0) lgkmcnt(0)
	v_lshlrev_b32_e32 v36, 16, v28
	v_lshlrev_b32_e32 v38, 16, v32
	v_and_b32_e32 v39, 0xffff0000, v32
	v_and_b32_e32 v37, 0xffff0000, v28
	v_pk_mul_f32 v[40:41], v[2:3], v[38:39]
	v_pk_mul_f32 v[38:39], v[8:9], v[38:39]
	v_lshlrev_b32_e32 v32, 16, v33
	v_and_b32_e32 v33, 0xffff0000, v33
	v_pk_fma_f32 v[40:41], v[8:9], v[36:37], v[40:41]
	v_pk_fma_f32 v[36:37], v[2:3], v[36:37], v[38:39] neg_lo:[0,0,1] neg_hi:[0,0,1]
	v_lshlrev_b32_e32 v28, 16, v29
	v_and_b32_e32 v29, 0xffff0000, v29
	v_pk_mul_f32 v[38:39], v[6:7], v[32:33]
	v_pk_mul_f32 v[32:33], v[12:13], v[32:33]
	v_lshlrev_b32_e32 v42, 16, v34
	v_and_b32_e32 v43, 0xffff0000, v34
	v_pk_fma_f32 v[38:39], v[12:13], v[28:29], v[38:39]
	v_pk_fma_f32 v[32:33], v[6:7], v[28:29], v[32:33] neg_lo:[0,0,1] neg_hi:[0,0,1]
	v_lshlrev_b32_e32 v28, 16, v30
	v_and_b32_e32 v29, 0xffff0000, v30
	v_pk_mul_f32 v[44:45], v[10:11], v[42:43]
	v_pk_mul_f32 v[42:43], v[16:17], v[42:43]
	v_pk_fma_f32 v[44:45], v[16:17], v[28:29], v[44:45]
	v_pk_fma_f32 v[42:43], v[10:11], v[28:29], v[42:43] neg_lo:[0,0,1] neg_hi:[0,0,1]
	v_lshlrev_b32_e32 v28, 16, v31
	v_and_b32_e32 v29, 0xffff0000, v31
	v_lshlrev_b32_e32 v30, 16, v35
	v_and_b32_e32 v31, 0xffff0000, v35
	v_pk_mul_f32 v[34:35], v[14:15], v[30:31]
	v_pk_mul_f32 v[30:31], v[24:25], v[30:31]
	v_pk_fma_f32 v[34:35], v[24:25], v[28:29], v[34:35]
	v_pk_fma_f32 v[46:47], v[14:15], v[28:29], v[30:31] neg_lo:[0,0,1] neg_hi:[0,0,1]
	v_cvt_pk_bf16_f32 v28, v36, v37
	v_cvt_pk_bf16_f32 v29, v32, v33
	v_cvt_pk_bf16_f32 v30, v42, v43
	v_cvt_pk_bf16_f32 v31, v46, v47
	global_store_dwordx4 v[4:5], v[28:31], off
	s_nop 1
	v_cvt_pk_bf16_f32 v28, v40, v41
	v_cvt_pk_bf16_f32 v29, v38, v39
	v_cvt_pk_bf16_f32 v30, v44, v45
	v_cvt_pk_bf16_f32 v31, v34, v35
	global_store_dwordx4 v[4:5], v[28:31], off offset:64
	s_branch .LBB0_332

.LBB0_462:
	s_and_b64 vcc, exec, s[4:5]
	s_cbranch_vccz .LBB0_438
	s_lshr_b32 s4, s12, 3
	s_mul_hi_u32 s5, s4, s59
	s_mul_i32 s6, s5, s37
	s_sub_i32 s6, s4, s6
	s_add_i32 s7, s5, 1
	s_sub_i32 s8, s6, s37
	s_cmp_ge_u32 s6, s37
	s_cselect_b32 s5, s7, s5
	s_cselect_b32 s6, s8, s6
	s_add_i32 s7, s5, 1
	s_cmp_ge_u32 s6, s37
	s_cselect_b32 s5, s7, s5
	s_mul_i32 s6, s5, s37
	s_sub_i32 s4, s4, s6
	s_mul_i32 s4, s4, s36
	v_mov_b32_e32 v195, v194
	s_add_i32 s4, s4, s80
	s_lshl_b32 s6, s12, 4
	s_and_b32 s24, s4, 1
	v_lshlrev_b32_e32 v0, 7, v195
	s_lshl_b32 s5, s5, 7
	s_and_b32 s6, s6, 0x70
	v_and_b32_e32 v0, 0x180, v0
	s_sub_i32 s76, s6, s5
	v_lshl_or_b32 v0, s24, 9, v0
	s_add_i32 s45, s76, 0xf80
	v_lshl_add_u64 v[6:7], v[154:155], 0, v[0:1]
	v_bfe_u32 v0, v195, 2, 3
	s_ashr_i32 s16, s4, 1
	v_ashrrev_i32_e32 v4, 5, v195
	v_or_b32_e32 v172, s45, v0
	s_ashr_i32 s17, s16, 31
	v_lshlrev_b32_e32 v2, 3, v4
	v_or_b32_e32 v174, 8, v172
	s_lshl_b64 s[6:7], s[16:17], 12
	v_ashrrev_i32_e32 v3, 31, v2
	v_ashrrev_i32_e32 v173, 31, v172
	v_ashrrev_i32_e32 v175, 31, v174
	v_lshl_add_u64 v[6:7], v[2:3], 1, v[6:7]
	v_lshl_add_u64 v[170:171], s[6:7], 0, v[172:173]
	v_lshl_add_u64 v[168:169], s[6:7], 0, v[174:175]
	v_mad_u64_u32 v[8:9], s[8:9], v170, s61, v[6:7]
	v_mad_u64_u32 v[6:7], s[6:7], v168, s61, v[6:7]
	v_mad_i32_i24 v9, v171, s61, v9
	v_mad_i32_i24 v7, v169, s61, v7
	global_load_dwordx4 v[82:85], v[8:9], off
	global_load_dwordx4 v[86:89], v[8:9], off offset:32
	global_load_dwordx4 v[90:93], v[8:9], off offset:64
	global_load_dwordx4 v[94:97], v[8:9], off offset:96
	global_load_dwordx4 v[98:101], v[6:7], off
	global_load_dwordx4 v[102:105], v[6:7], off offset:32
	global_load_dwordx4 v[106:109], v[6:7], off offset:64
	global_load_dwordx4 v[110:113], v[6:7], off offset:96
	s_mov_b32 s100, 0xf9800000
	s_mov_b32 s101, -1
	v_lshlrev_b32_e32 v140, 8, v170
	v_lshl_add_u32 v140, v2, 3, v140
	v_mov_b32_e32 v141, 0
	v_lshl_add_u64 v[140:141], v[154:155], 0, v[140:141]
	v_lshl_add_u64 v[140:141], v[140:141], 0, s[100:101]
	global_load_dwordx4 v[16:19], v[140:141], off offset:0
	global_load_dwordx4 v[20:23], v[140:141], off offset:16
	global_load_dwordx4 v[24:27], v[140:141], off offset:32
	global_load_dwordx4 v[28:31], v[140:141], off offset:48
	global_load_dwordx4 v[32:35], v[140:141], off offset:128
	global_load_dwordx4 v[36:39], v[140:141], off offset:144
	global_load_dwordx4 v[40:43], v[140:141], off offset:160
	global_load_dwordx4 v[44:47], v[140:141], off offset:176
	v_lshlrev_b32_e32 v140, 8, v168
	v_lshl_add_u32 v140, v2, 3, v140
	v_mov_b32_e32 v141, 0
	v_lshl_add_u64 v[140:141], v[154:155], 0, v[140:141]
	v_lshl_add_u64 v[140:141], v[140:141], 0, s[100:101]
	global_load_dwordx4 v[48:51], v[140:141], off offset:0
	global_load_dwordx4 v[52:55], v[140:141], off offset:16
	global_load_dwordx4 v[56:59], v[140:141], off offset:32
	global_load_dwordx4 v[60:63], v[140:141], off offset:48
	global_load_dwordx4 v[66:69], v[140:141], off offset:128
	global_load_dwordx4 v[70:73], v[140:141], off offset:144
	global_load_dwordx4 v[74:77], v[140:141], off offset:160
	global_load_dwordx4 v[78:81], v[140:141], off offset:176
	s_ashr_i32 s5, s4, 31
	s_lshl_b64 s[4:5], s[4:5], 15
	s_add_i32 s8, s76, 0xf70
	s_cmp_gt_i32 s45, 15
	s_cselect_b64 s[6:7], -1, 0
	s_lshr_b32 s10, s8, 9
	s_waitcnt vmcnt(0)
	v_lshlrev_b32_e32 v130, 16, v82
	v_and_b32_e32 v131, 0xffff0000, v82
	v_lshlrev_b32_e32 v132, 16, v90
	v_and_b32_e32 v133, 0xffff0000, v90
	v_mul_f32_e32 v134, v17, v132
	v_mul_f32_e32 v135, v19, v133
	v_mul_f32_e32 v136, v16, v132
	v_mul_f32_e32 v137, v18, v133
	v_fma_f32 v134, v16, v130, -v134
	v_fma_f32 v135, v18, v131, -v135
	v_fma_f32 v136, v17, v130, v136
	v_fma_f32 v137, v19, v131, v137
	v_cvt_pk_bf16_f32 v82, v134, v135
	v_cvt_pk_bf16_f32 v90, v136, v137
	v_lshlrev_b32_e32 v130, 16, v83
	v_and_b32_e32 v131, 0xffff0000, v83
	v_lshlrev_b32_e32 v132, 16, v91
	v_and_b32_e32 v133, 0xffff0000, v91
	v_mul_f32_e32 v134, v21, v132
	v_mul_f32_e32 v135, v23, v133
	v_mul_f32_e32 v136, v20, v132
	v_mul_f32_e32 v137, v22, v133
	v_fma_f32 v134, v20, v130, -v134
	v_fma_f32 v135, v22, v131, -v135
	v_fma_f32 v136, v21, v130, v136
	v_fma_f32 v137, v23, v131, v137
	v_cvt_pk_bf16_f32 v83, v134, v135
	v_cvt_pk_bf16_f32 v91, v136, v137
	v_lshlrev_b32_e32 v130, 16, v84
	v_and_b32_e32 v131, 0xffff0000, v84
	v_lshlrev_b32_e32 v132, 16, v92
	v_and_b32_e32 v133, 0xffff0000, v92
	v_mul_f32_e32 v134, v25, v132
	v_mul_f32_e32 v135, v27, v133
	v_mul_f32_e32 v136, v24, v132
	v_mul_f32_e32 v137, v26, v133
	v_fma_f32 v134, v24, v130, -v134
	v_fma_f32 v135, v26, v131, -v135
	v_fma_f32 v136, v25, v130, v136
	v_fma_f32 v137, v27, v131, v137
	v_cvt_pk_bf16_f32 v84, v134, v135
	v_cvt_pk_bf16_f32 v92, v136, v137
	v_lshlrev_b32_e32 v130, 16, v85
	v_and_b32_e32 v131, 0xffff0000, v85
	v_lshlrev_b32_e32 v132, 16, v93
	v_and_b32_e32 v133, 0xffff0000, v93
	v_mul_f32_e32 v134, v29, v132
	v_mul_f32_e32 v135, v31, v133
	v_mul_f32_e32 v136, v28, v132
	v_mul_f32_e32 v137, v30, v133
	v_fma_f32 v134, v28, v130, -v134
	v_fma_f32 v135, v30, v131, -v135
	v_fma_f32 v136, v29, v130, v136
	v_fma_f32 v137, v31, v131, v137
	v_cvt_pk_bf16_f32 v85, v134, v135
	v_cvt_pk_bf16_f32 v93, v136, v137
	v_lshlrev_b32_e32 v130, 16, v86
	v_and_b32_e32 v131, 0xffff0000, v86
	v_lshlrev_b32_e32 v132, 16, v94
	v_and_b32_e32 v133, 0xffff0000, v94
	v_mul_f32_e32 v134, v33, v132
	v_mul_f32_e32 v135, v35, v133
	v_mul_f32_e32 v136, v32, v132
	v_mul_f32_e32 v137, v34, v133
	v_fma_f32 v134, v32, v130, -v134
	v_fma_f32 v135, v34, v131, -v135
	v_fma_f32 v136, v33, v130, v136
	v_fma_f32 v137, v35, v131, v137
	v_cvt_pk_bf16_f32 v86, v134, v135
	v_cvt_pk_bf16_f32 v94, v136, v137
	v_lshlrev_b32_e32 v130, 16, v87
	v_and_b32_e32 v131, 0xffff0000, v87
	v_lshlrev_b32_e32 v132, 16, v95
	v_and_b32_e32 v133, 0xffff0000, v95
	v_mul_f32_e32 v134, v37, v132
	v_mul_f32_e32 v135, v39, v133
	v_mul_f32_e32 v136, v36, v132
	v_mul_f32_e32 v137, v38, v133
	v_fma_f32 v134, v36, v130, -v134
	v_fma_f32 v135, v38, v131, -v135
	v_fma_f32 v136, v37, v130, v136
	v_fma_f32 v137, v39, v131, v137
	v_cvt_pk_bf16_f32 v87, v134, v135
	v_cvt_pk_bf16_f32 v95, v136, v137
	v_lshlrev_b32_e32 v130, 16, v88
	v_and_b32_e32 v131, 0xffff0000, v88
	v_lshlrev_b32_e32 v132, 16, v96
	v_and_b32_e32 v133, 0xffff0000, v96
	v_mul_f32_e32 v134, v41, v132
	v_mul_f32_e32 v135, v43, v133
	v_mul_f32_e32 v136, v40, v132
	v_mul_f32_e32 v137, v42, v133
	v_fma_f32 v134, v40, v130, -v134
	v_fma_f32 v135, v42, v131, -v135
	v_fma_f32 v136, v41, v130, v136
	v_fma_f32 v137, v43, v131, v137
	v_cvt_pk_bf16_f32 v88, v134, v135
	v_cvt_pk_bf16_f32 v96, v136, v137
	v_lshlrev_b32_e32 v130, 16, v89
	v_and_b32_e32 v131, 0xffff0000, v89
	v_lshlrev_b32_e32 v132, 16, v97
	v_and_b32_e32 v133, 0xffff0000, v97
	v_mul_f32_e32 v134, v45, v132
	v_mul_f32_e32 v135, v47, v133
	v_mul_f32_e32 v136, v44, v132
	v_mul_f32_e32 v137, v46, v133
	v_fma_f32 v134, v44, v130, -v134
	v_fma_f32 v135, v46, v131, -v135
	v_fma_f32 v136, v45, v130, v136
	v_fma_f32 v137, v47, v131, v137
	v_cvt_pk_bf16_f32 v89, v134, v135
	v_cvt_pk_bf16_f32 v97, v136, v137
	v_lshlrev_b32_e32 v130, 16, v98
	v_and_b32_e32 v131, 0xffff0000, v98
	v_lshlrev_b32_e32 v132, 16, v106
	v_and_b32_e32 v133, 0xffff0000, v106
	v_mul_f32_e32 v134, v49, v132
	v_mul_f32_e32 v135, v51, v133
	v_mul_f32_e32 v136, v48, v132
	v_mul_f32_e32 v137, v50, v133
	v_fma_f32 v134, v48, v130, -v134
	v_fma_f32 v135, v50, v131, -v135
	v_fma_f32 v136, v49, v130, v136
	v_fma_f32 v137, v51, v131, v137
	v_cvt_pk_bf16_f32 v98, v134, v135
	v_cvt_pk_bf16_f32 v106, v136, v137
	v_lshlrev_b32_e32 v130, 16, v99
	v_and_b32_e32 v131, 0xffff0000, v99
	v_lshlrev_b32_e32 v132, 16, v107
	v_and_b32_e32 v133, 0xffff0000, v107
	v_mul_f32_e32 v134, v53, v132
	v_mul_f32_e32 v135, v55, v133
	v_mul_f32_e32 v136, v52, v132
	v_mul_f32_e32 v137, v54, v133
	v_fma_f32 v134, v52, v130, -v134
	v_fma_f32 v135, v54, v131, -v135
	v_fma_f32 v136, v53, v130, v136
	v_fma_f32 v137, v55, v131, v137
	v_cvt_pk_bf16_f32 v99, v134, v135
	v_cvt_pk_bf16_f32 v107, v136, v137
	v_lshlrev_b32_e32 v130, 16, v100
	v_and_b32_e32 v131, 0xffff0000, v100
	v_lshlrev_b32_e32 v132, 16, v108
	v_and_b32_e32 v133, 0xffff0000, v108
	v_mul_f32_e32 v134, v57, v132
	v_mul_f32_e32 v135, v59, v133
	v_mul_f32_e32 v136, v56, v132
	v_mul_f32_e32 v137, v58, v133
	v_fma_f32 v134, v56, v130, -v134
	v_fma_f32 v135, v58, v131, -v135
	v_fma_f32 v136, v57, v130, v136
	v_fma_f32 v137, v59, v131, v137
	v_cvt_pk_bf16_f32 v100, v134, v135
	v_cvt_pk_bf16_f32 v108, v136, v137
	v_lshlrev_b32_e32 v130, 16, v101
	v_and_b32_e32 v131, 0xffff0000, v101
	v_lshlrev_b32_e32 v132, 16, v109
	v_and_b32_e32 v133, 0xffff0000, v109
	v_mul_f32_e32 v134, v61, v132
	v_mul_f32_e32 v135, v63, v133
	v_mul_f32_e32 v136, v60, v132
	v_mul_f32_e32 v137, v62, v133
	v_fma_f32 v134, v60, v130, -v134
	v_fma_f32 v135, v62, v131, -v135
	v_fma_f32 v136, v61, v130, v136
	v_fma_f32 v137, v63, v131, v137
	v_cvt_pk_bf16_f32 v101, v134, v135
	v_cvt_pk_bf16_f32 v109, v136, v137
	v_lshlrev_b32_e32 v130, 16, v102
	v_and_b32_e32 v131, 0xffff0000, v102
	v_lshlrev_b32_e32 v132, 16, v110
	v_and_b32_e32 v133, 0xffff0000, v110
	v_mul_f32_e32 v134, v67, v132
	v_mul_f32_e32 v135, v69, v133
	v_mul_f32_e32 v136, v66, v132
	v_mul_f32_e32 v137, v68, v133
	v_fma_f32 v134, v66, v130, -v134
	v_fma_f32 v135, v68, v131, -v135
	v_fma_f32 v136, v67, v130, v136
	v_fma_f32 v137, v69, v131, v137
	v_cvt_pk_bf16_f32 v102, v134, v135
	v_cvt_pk_bf16_f32 v110, v136, v137
	v_lshlrev_b32_e32 v130, 16, v103
	v_and_b32_e32 v131, 0xffff0000, v103
	v_lshlrev_b32_e32 v132, 16, v111
	v_and_b32_e32 v133, 0xffff0000, v111
	v_mul_f32_e32 v134, v71, v132
	v_mul_f32_e32 v135, v73, v133
	v_mul_f32_e32 v136, v70, v132
	v_mul_f32_e32 v137, v72, v133
	v_fma_f32 v134, v70, v130, -v134
	v_fma_f32 v135, v72, v131, -v135
	v_fma_f32 v136, v71, v130, v136
	v_fma_f32 v137, v73, v131, v137
	v_cvt_pk_bf16_f32 v103, v134, v135
	v_cvt_pk_bf16_f32 v111, v136, v137
	v_lshlrev_b32_e32 v130, 16, v104
	v_and_b32_e32 v131, 0xffff0000, v104
	v_lshlrev_b32_e32 v132, 16, v112
	v_and_b32_e32 v133, 0xffff0000, v112
	v_mul_f32_e32 v134, v75, v132
	v_mul_f32_e32 v135, v77, v133
	v_mul_f32_e32 v136, v74, v132
	v_mul_f32_e32 v137, v76, v133
	v_fma_f32 v134, v74, v130, -v134
	v_fma_f32 v135, v76, v131, -v135
	v_fma_f32 v136, v75, v130, v136
	v_fma_f32 v137, v77, v131, v137
	v_cvt_pk_bf16_f32 v104, v134, v135
	v_cvt_pk_bf16_f32 v112, v136, v137
	v_lshlrev_b32_e32 v130, 16, v105
	v_and_b32_e32 v131, 0xffff0000, v105
	v_lshlrev_b32_e32 v132, 16, v113
	v_and_b32_e32 v133, 0xffff0000, v113
	v_mul_f32_e32 v134, v79, v132
	v_mul_f32_e32 v135, v81, v133
	v_mul_f32_e32 v136, v78, v132
	v_mul_f32_e32 v137, v80, v133
	v_fma_f32 v134, v78, v130, -v134
	v_fma_f32 v135, v80, v131, -v135
	v_fma_f32 v136, v79, v130, v136
	v_fma_f32 v137, v81, v131, v137
	v_cvt_pk_bf16_f32 v105, v134, v135
	v_cvt_pk_bf16_f32 v113, v136, v137
	s_cmp_lt_i32 s45, 16
	s_cbranch_scc1 .LBB0_477
	v_and_b32_e32 v5, 31, v195
	v_lshl_add_u64 v[6:7], v[156:157], 0, s[4:5]
	v_lshlrev_b32_e32 v0, 7, v5
	v_lshl_add_u64 v[6:7], v[6:7], 0, v[0:1]
	v_lshlrev_b64 v[2:3], 1, v[2:3]
	v_lshl_add_u64 v[148:149], v[6:7], 0, v[2:3]
	global_load_dwordx4 v[114:117], v[148:149], off offset:96
	global_load_dwordx4 v[118:121], v[148:149], off offset:64
	global_load_dwordx4 v[122:125], v[148:149], off offset:32
	global_load_dwordx4 v[126:129], v[148:149], off
	v_lshl_add_u64 v[6:7], v[158:159], 0, s[4:5]
	v_lshl_add_u64 v[2:3], v[6:7], 0, v[2:3]
	v_lshlrev_b32_e32 v0, 5, v5
	v_mov_b32_e32 v14, v1
	v_mov_b32_e32 v15, v1
	v_lshl_add_u64 v[150:151], v[2:3], 0, v[0:1]
	v_lshlrev_b32_e32 v152, 6, v4
	v_mov_b32_e32 v0, v1
	v_mov_b32_e32 v2, v1
	v_mov_b32_e32 v3, v1
	v_mov_b32_e32 v4, v1
	v_mov_b32_e32 v5, v1
	v_mov_b32_e32 v6, v1
	v_mov_b32_e32 v7, v1
	v_mov_b32_e32 v8, v1
	v_mov_b32_e32 v9, v1
	v_mov_b32_e32 v10, v1
	v_mov_b32_e32 v11, v1
	v_mov_b32_e32 v12, v1
	v_mov_b32_e32 v13, v1
	v_mov_b64_e32 v[64:65], v[14:15]
	v_mov_b64_e32 v[80:81], v[14:15]
	v_mov_b64_e32 v[48:49], v[14:15]
	v_mov_b64_e32 v[32:33], v[14:15]
	s_mov_b32 s11, 0
	v_mov_b32_e32 v153, 0xf149f2ca
	v_mov_b32_e32 v147, 0
	s_movk_i32 s12, 0x20f
	v_mov_b32_e32 v146, 0
	v_mov_b32_e32 v173, 0xf149f2ca
	v_mov_b32_e32 v189, 0xf149f2ca
	v_mov_b64_e32 v[62:63], v[12:13]
	v_mov_b64_e32 v[60:61], v[10:11]
	v_mov_b64_e32 v[58:59], v[8:9]
	v_mov_b64_e32 v[56:57], v[6:7]
	v_mov_b64_e32 v[54:55], v[4:5]
	v_mov_b64_e32 v[52:53], v[2:3]
	v_mov_b64_e32 v[50:51], v[0:1]
	v_mov_b64_e32 v[78:79], v[12:13]
	v_mov_b64_e32 v[76:77], v[10:11]
	v_mov_b64_e32 v[74:75], v[8:9]
	v_mov_b64_e32 v[72:73], v[6:7]
	v_mov_b64_e32 v[70:71], v[4:5]
	v_mov_b64_e32 v[68:69], v[2:3]
	v_mov_b64_e32 v[66:67], v[0:1]
	v_mov_b32_e32 v175, 0xf149f2ca
	v_mov_b64_e32 v[46:47], v[12:13]
	v_mov_b64_e32 v[44:45], v[10:11]
	v_mov_b64_e32 v[42:43], v[8:9]
	v_mov_b64_e32 v[40:41], v[6:7]
	v_mov_b64_e32 v[38:39], v[4:5]
	v_mov_b64_e32 v[36:37], v[2:3]
	v_mov_b64_e32 v[34:35], v[0:1]
	v_mov_b64_e32 v[30:31], v[12:13]
	v_mov_b64_e32 v[28:29], v[10:11]
	v_mov_b64_e32 v[26:27], v[8:9]
	v_mov_b64_e32 v[24:25], v[6:7]
	v_mov_b64_e32 v[22:23], v[4:5]
	v_mov_b64_e32 v[20:21], v[2:3]
	v_mov_b64_e32 v[18:19], v[0:1]
